# E1 pooling loop: window groups of waves 4-7 mirrored (gi -> 3-gi) so each SIMD hosts one heavy and one light window group
# speedup vs baseline: 1.0015x; 1.0015x over previous
; __device__ __forceinline__ void unpack8(const u32x4 w, f32x4& v0, f32x4& v1) { v0 = (f32x4){bflo(w.x), bfhi(w.x), bflo(w.y), bfhi(w.y)}; v1 = (f32x4){bflo(w.z), bfhi(w.z), bflo(w.w), bfhi(w.w)}; }
; __device__ __forceinline__ Tok tok_decode(int tok) { Tok r; if (tok < T_P) { r.is_s = 0; r.seq = tok >> 11; r.t = tok & 2047; } else { r.is_s = 1; r.seq = (tok - T_P) >> 3; r.t = (tok - T_P) & 7; } return r; }
; #define POOL_ROWS(W) { u32x4 rw[W - 1]; \
;             _Pragma("unroll") for (int j = 1; j < W; ++j) rw[j - 1] = *(const u32x4*)(zr - (size_t)(tk.t - j >= 0 ? j : 0) * DIN); \
;             _Pragma("unroll") for (int j = 1; j < W; ++j) { f32x4 a0, a1; unpack8(rw[j - 1], a0, a1); const float mk = (tk.t - j >= 0) ? 1.0f : 0.0f; s0 += a0 * mk; s1 += a1 * mk; } }
; __device__ void phase_e1(int l) {
;     ...
;     for (int it = gtid; it < T_ALL * 64; it += nth) {
;         const int gi = (it >> 6) & 3, tok = (it >> 8) * 4 + ((it >> 4) & 3), c = gi * 128 + (it & 15) * 8, win = 2 << gi; const Tok tk = tok_decode(tok);
;         const bf16_t* zr = z + (size_t)tok * DIN + O_U + c;
;         f32x4 u0, u1; unpack8(*(const u32x4*)zr, u0, u1);
;         f32x4 s0 = u0, s1 = u1;
;     ...
;         if (gi == 0) POOL_ROWS(2) else if (gi == 1) POOL_ROWS(4) else if (gi == 2) POOL_ROWS(8) else POOL_ROWS(16)
.LBB0_238:
	v_ashrrev_i32_e32 v17, 6, v51
	v_lshrrev_b32_e32 v0, 4, v51
	v_bfi_b32 v16, -4, v17, v0
	v_lshlrev_b32_e32 v0, 3, v51
	v_cmp_gt_i32_e32 vcc, s7, v16
	v_bfe_u32 v53, v51, 6, 2
	v_bfe_i32 v255, v51, 8, 1
	v_and_b32_e32 v255, 3, v255
	v_xor_b32_e32 v53, v53, v255
	s_waitcnt vmcnt(1)
	v_and_b32_e32 v4, -4, v17
	v_and_b32_e32 v0, 0x78, v0
	v_bfe_u32 v5, v51, 4, 2
	v_cndmask_b32_e32 v6, 7, v35, vcc
	v_lshl_or_b32 v52, v53, 7, v0
	v_bitop3_b32 v54, v6, v4, v5 bitop3:0xe0
	v_mad_i64_i32 v[0:1], s[8:9], v16, s33, v[12:13]
	v_lshlrev_b32_e32 v14, 1, v52
	v_cmp_eq_u32_e64 s[10:11], 0, v54
	v_lshl_add_u64 v[26:27], v[0:1], 0, v[14:15]
	global_load_dwordx4 v[0:3], v[26:27], off offset:3584
	v_cndmask_b32_e64 v5, -1, 0, s[10:11]
	v_cndmask_b32_e64 v4, v36, 0, s[10:11]
	v_lshl_add_u64 v[4:5], v[26:27], 0, v[4:5]
	global_load_dwordx4 v[8:11], v[4:5], off offset:3584
	v_cmp_lt_i32_e64 s[8:9], s6, v16
	v_cmp_lt_i32_e64 s[12:13], 1, v53
	s_waitcnt vmcnt(1)
	v_lshlrev_b32_e32 v20, 16, v0
	v_and_b32_e32 v21, 0xffff0000, v0
	v_lshlrev_b32_e32 v24, 16, v1
	v_and_b32_e32 v25, 0xffff0000, v1
	v_lshlrev_b32_e32 v18, 16, v2
	v_and_b32_e32 v19, 0xffff0000, v2
	v_lshlrev_b32_e32 v22, 16, v3
	v_and_b32_e32 v23, 0xffff0000, v3
	s_and_saveexec_b64 s[14:15], s[12:13]
	s_xor_b64 s[70:71], exec, s[14:15]
	s_cbranch_execz .LBB0_244
	v_cmp_lt_i32_e64 s[12:13], 2, v53
	s_and_saveexec_b64 s[14:15], s[12:13]
	s_xor_b64 s[72:73], exec, s[14:15]
	s_cbranch_execz .LBB0_241
	v_cmp_gt_u32_e64 s[40:41], 2, v54
	v_cmp_gt_u32_e64 s[36:37], 4, v54
	v_cmp_gt_u32_e64 s[38:39], 3, v54
	v_cndmask_b32_e64 v1, -1, 0, s[40:41]
	v_cndmask_b32_e64 v0, v37, 0, s[40:41]
	v_cndmask_b32_e64 v3, -1, 0, s[36:37]
	v_cndmask_b32_e64 v2, v39, 0, s[36:37]
	v_lshl_add_u64 v[0:1], v[26:27], 0, v[0:1]
	v_lshl_add_u64 v[2:3], v[26:27], 0, v[2:3]
	global_load_dwordx4 v[28:31], v[0:1], off offset:3584
	global_load_dwordx4 v[60:63], v[2:3], off offset:3584
	v_cndmask_b32_e64 v1, -1, 0, s[38:39]
	v_cndmask_b32_e64 v0, v38, 0, s[38:39]
	v_cmp_gt_u32_e64 s[34:35], 5, v54
	v_lshl_add_u64 v[0:1], v[26:27], 0, v[0:1]
	v_cmp_gt_u32_e64 s[30:31], 6, v54
	v_cndmask_b32_e64 v5, -1, 0, s[34:35]
	global_load_dwordx4 v[56:59], v[0:1], off offset:3584
	v_cndmask_b32_e64 v4, v40, 0, s[34:35]
	v_cndmask_b32_e64 v7, -1, 0, s[30:31]
	v_cmp_gt_u32_e64 s[28:29], 7, v54
	v_lshl_add_u64 v[4:5], v[26:27], 0, v[4:5]
	v_cndmask_b32_e64 v6, v41, 0, s[30:31]
	v_cmp_gt_u32_e64 s[24:25], 9, v54
	global_load_dwordx4 v[64:67], v[4:5], off offset:3584
	v_cndmask_b32_e64 v1, -1, 0, s[28:29]
	v_cndmask_b32_e64 v0, v42, 0, s[28:29]
	v_lshl_add_u64 v[6:7], v[26:27], 0, v[6:7]
	v_cndmask_b32_e64 v69, -1, 0, s[24:25]
	s_waitcnt vmcnt(4)
	v_lshlrev_b32_e32 v70, 16, v8
	v_and_b32_e32 v71, 0xffff0000, v8
	v_lshlrev_b32_e32 v82, 16, v9
	v_and_b32_e32 v83, 0xffff0000, v9
	v_lshlrev_b32_e32 v4, 16, v10
	v_and_b32_e32 v5, 0xffff0000, v10
	v_lshlrev_b32_e32 v84, 16, v11
	v_and_b32_e32 v85, 0xffff0000, v11
	v_cndmask_b32_e64 v86, 1.0, 0, s[10:11]
	v_cndmask_b32_e64 v68, v44, 0, s[24:25]
	global_load_dwordx4 v[8:11], v[6:7], off offset:3584
	v_lshl_add_u64 v[0:1], v[26:27], 0, v[0:1]
	v_pk_fma_f32 v[98:99], v[86:87], v[70:71], v[20:21] op_sel_hi:[0,1,1]
	v_lshl_add_u64 v[6:7], v[26:27], 0, v[68:69]
	global_load_dwordx4 v[68:71], v[0:1], off offset:3584
	v_cmp_gt_u32_e64 s[26:27], 8, v54
	v_cmp_gt_u32_e64 s[22:23], 10, v54
	v_cmp_gt_u32_e64 s[18:19], 12, v54
	v_cmp_gt_u32_e64 s[16:17], 13, v54
	v_cndmask_b32_e64 v33, -1, 0, s[26:27]
	v_cndmask_b32_e64 v73, -1, 0, s[22:23]
	v_cmp_gt_u32_e64 s[20:21], 11, v54
	v_cndmask_b32_e64 v3, -1, 0, s[18:19]
	v_cndmask_b32_e64 v77, -1, 0, s[16:17]
	v_cmp_gt_u32_e64 s[14:15], 14, v54
	v_cmp_gt_u32_e64 s[12:13], 15, v54
	v_cndmask_b32_e64 v32, v43, 0, s[26:27]
	v_cndmask_b32_e64 v72, v45, 0, s[22:23]
	v_cndmask_b32_e64 v2, v47, 0, s[18:19]
	v_cndmask_b32_e64 v76, v48, 0, s[16:17]
	v_cndmask_b32_e64 v75, -1, 0, s[20:21]
	v_cndmask_b32_e64 v79, -1, 0, s[14:15]
	v_cndmask_b32_e64 v81, -1, 0, s[12:13]
	v_cndmask_b32_e64 v74, v46, 0, s[20:21]
	v_cndmask_b32_e64 v78, v49, 0, s[14:15]
	v_cndmask_b32_e64 v80, v50, 0, s[12:13]
	v_pk_fma_f32 v[102:103], v[86:87], v[4:5], v[18:19] op_sel_hi:[0,1,1]
	v_lshl_add_u64 v[4:5], v[26:27], 0, v[32:33]
	v_lshl_add_u64 v[0:1], v[26:27], 0, v[72:73]
	v_lshl_add_u64 v[2:3], v[26:27], 0, v[2:3]
	v_lshl_add_u64 v[92:93], v[26:27], 0, v[76:77]
	v_pk_fma_f32 v[96:97], v[86:87], v[82:83], v[24:25] op_sel_hi:[0,1,1]
	v_pk_fma_f32 v[100:101], v[86:87], v[84:85], v[22:23] op_sel_hi:[0,1,1]
	v_lshl_add_u64 v[32:33], v[26:27], 0, v[74:75]
	v_lshl_add_u64 v[104:105], v[26:27], 0, v[78:79]
	v_lshl_add_u64 v[26:27], v[26:27], 0, v[80:81]
	global_load_dwordx4 v[72:75], v[4:5], off offset:3584
	global_load_dwordx4 v[76:79], v[6:7], off offset:3584
	global_load_dwordx4 v[80:83], v[0:1], off offset:3584
	global_load_dwordx4 v[84:87], v[32:33], off offset:3584
	global_load_dwordx4 v[88:91], v[2:3], off offset:3584
	s_nop 0
	global_load_dwordx4 v[92:95], v[92:93], off offset:3584
	s_nop 0
	global_load_dwordx4 v[4:7], v[104:105], off offset:3584
	global_load_dwordx4 v[0:3], v[26:27], off offset:3584
	v_cndmask_b32_e64 v104, 1.0, 0, s[40:41]
	s_waitcnt vmcnt(13)
	v_lshlrev_b32_e32 v26, 16, v28
	v_and_b32_e32 v27, 0xffff0000, v28
	v_lshlrev_b32_e32 v28, 16, v29
	v_and_b32_e32 v29, 0xffff0000, v29
	v_lshlrev_b32_e32 v32, 16, v30
	v_and_b32_e32 v33, 0xffff0000, v30
	v_lshlrev_b32_e32 v30, 16, v31
	v_and_b32_e32 v31, 0xffff0000, v31
	v_pk_fma_f32 v[26:27], v[104:105], v[26:27], v[98:99] op_sel_hi:[0,1,1]
	v_pk_fma_f32 v[28:29], v[104:105], v[28:29], v[96:97] op_sel_hi:[0,1,1]
	v_pk_fma_f32 v[32:33], v[104:105], v[32:33], v[102:103] op_sel_hi:[0,1,1]
	v_pk_fma_f32 v[30:31], v[104:105], v[30:31], v[100:101] op_sel_hi:[0,1,1]
	s_waitcnt vmcnt(11)
; #define POOL_ROWS(W) { u32x4 rw[W - 1]; \
;             _Pragma("unroll") for (int j = 1; j < W; ++j) rw[j - 1] = *(const u32x4*)(zr - (size_t)(tk.t - j >= 0 ? j : 0) * DIN); \
;             _Pragma("unroll") for (int j = 1; j < W; ++j) { f32x4 a0, a1; unpack8(rw[j - 1], a0, a1); const float mk = (tk.t - j >= 0) ? 1.0f : 0.0f; s0 += a0 * mk; s1 += a1 * mk; } }
; __device__ void phase_e1(int l) {
;     ...
;         if (gi == 0) POOL_ROWS(2) else if (gi == 1) POOL_ROWS(4) else if (gi == 2) POOL_ROWS(8) else POOL_ROWS(16)
	v_lshlrev_b32_e32 v96, 16, v56
	v_and_b32_e32 v97, 0xffff0000, v56
	v_lshlrev_b32_e32 v56, 16, v57
	v_and_b32_e32 v57, 0xffff0000, v57
	v_lshlrev_b32_e32 v98, 16, v58
	v_and_b32_e32 v99, 0xffff0000, v58
	v_lshlrev_b32_e32 v58, 16, v59
	v_and_b32_e32 v59, 0xffff0000, v59
	v_cndmask_b32_e64 v100, 1.0, 0, s[38:39]
	v_pk_fma_f32 v[28:29], v[100:101], v[56:57], v[28:29] op_sel_hi:[0,1,1]
	v_pk_fma_f32 v[26:27], v[100:101], v[96:97], v[26:27] op_sel_hi:[0,1,1]
	v_pk_fma_f32 v[30:31], v[100:101], v[58:59], v[30:31] op_sel_hi:[0,1,1]
	v_pk_fma_f32 v[32:33], v[100:101], v[98:99], v[32:33] op_sel_hi:[0,1,1]
	v_lshlrev_b32_e32 v56, 16, v60
	v_and_b32_e32 v57, 0xffff0000, v60
	v_lshlrev_b32_e32 v58, 16, v61
	v_and_b32_e32 v59, 0xffff0000, v61
	v_lshlrev_b32_e32 v60, 16, v62
	v_and_b32_e32 v61, 0xffff0000, v62
	v_lshlrev_b32_e32 v62, 16, v63
	v_and_b32_e32 v63, 0xffff0000, v63
	v_cndmask_b32_e64 v96, 1.0, 0, s[36:37]
	v_pk_fma_f32 v[26:27], v[96:97], v[56:57], v[26:27] op_sel_hi:[0,1,1]
	v_pk_fma_f32 v[28:29], v[96:97], v[58:59], v[28:29] op_sel_hi:[0,1,1]
	v_pk_fma_f32 v[32:33], v[96:97], v[60:61], v[32:33] op_sel_hi:[0,1,1]
	v_pk_fma_f32 v[30:31], v[96:97], v[62:63], v[30:31] op_sel_hi:[0,1,1]
	s_waitcnt vmcnt(10)
	v_lshlrev_b32_e32 v56, 16, v64
	v_and_b32_e32 v57, 0xffff0000, v64
	v_lshlrev_b32_e32 v58, 16, v65
	v_and_b32_e32 v59, 0xffff0000, v65
	v_lshlrev_b32_e32 v60, 16, v66
	v_and_b32_e32 v61, 0xffff0000, v66
	v_lshlrev_b32_e32 v62, 16, v67
	v_and_b32_e32 v63, 0xffff0000, v67
	v_cndmask_b32_e64 v64, 1.0, 0, s[34:35]
	v_pk_fma_f32 v[28:29], v[64:65], v[58:59], v[28:29] op_sel_hi:[0,1,1]
	v_pk_fma_f32 v[26:27], v[64:65], v[56:57], v[26:27] op_sel_hi:[0,1,1]
	v_pk_fma_f32 v[30:31], v[64:65], v[62:63], v[30:31] op_sel_hi:[0,1,1]
	v_pk_fma_f32 v[32:33], v[64:65], v[60:61], v[32:33] op_sel_hi:[0,1,1]
	s_waitcnt vmcnt(9)
	v_lshlrev_b32_e32 v56, 16, v8
	v_and_b32_e32 v57, 0xffff0000, v8
	v_lshlrev_b32_e32 v8, 16, v9
	v_and_b32_e32 v9, 0xffff0000, v9
	v_lshlrev_b32_e32 v58, 16, v10
	v_and_b32_e32 v59, 0xffff0000, v10
	v_lshlrev_b32_e32 v10, 16, v11
	v_and_b32_e32 v11, 0xffff0000, v11
	v_cndmask_b32_e64 v60, 1.0, 0, s[30:31]
	v_pk_fma_f32 v[26:27], v[60:61], v[56:57], v[26:27] op_sel_hi:[0,1,1]
	v_pk_fma_f32 v[8:9], v[60:61], v[8:9], v[28:29] op_sel_hi:[0,1,1]
	v_pk_fma_f32 v[28:29], v[60:61], v[58:59], v[32:33] op_sel_hi:[0,1,1]
	v_pk_fma_f32 v[10:11], v[60:61], v[10:11], v[30:31] op_sel_hi:[0,1,1]
	s_waitcnt vmcnt(8)
	v_lshlrev_b32_e32 v30, 16, v68
	v_and_b32_e32 v31, 0xffff0000, v68
	v_lshlrev_b32_e32 v32, 16, v69
	v_and_b32_e32 v33, 0xffff0000, v69
	v_lshlrev_b32_e32 v56, 16, v70
	v_and_b32_e32 v57, 0xffff0000, v70
	v_lshlrev_b32_e32 v58, 16, v71
	v_and_b32_e32 v59, 0xffff0000, v71
	v_cndmask_b32_e64 v60, 1.0, 0, s[28:29]
	v_pk_fma_f32 v[8:9], v[60:61], v[32:33], v[8:9] op_sel_hi:[0,1,1]
	v_pk_fma_f32 v[26:27], v[60:61], v[30:31], v[26:27] op_sel_hi:[0,1,1]
	v_pk_fma_f32 v[10:11], v[60:61], v[58:59], v[10:11] op_sel_hi:[0,1,1]
	v_pk_fma_f32 v[28:29], v[60:61], v[56:57], v[28:29] op_sel_hi:[0,1,1]
	s_waitcnt vmcnt(7)
	v_lshlrev_b32_e32 v30, 16, v72
	v_and_b32_e32 v31, 0xffff0000, v72
	v_lshlrev_b32_e32 v32, 16, v73
	v_and_b32_e32 v33, 0xffff0000, v73
	v_lshlrev_b32_e32 v56, 16, v74
	v_and_b32_e32 v57, 0xffff0000, v74
	v_lshlrev_b32_e32 v58, 16, v75
	v_and_b32_e32 v59, 0xffff0000, v75
	v_cndmask_b32_e64 v60, 1.0, 0, s[26:27]
	v_pk_fma_f32 v[26:27], v[60:61], v[30:31], v[26:27] op_sel_hi:[0,1,1]
	v_pk_fma_f32 v[8:9], v[60:61], v[32:33], v[8:9] op_sel_hi:[0,1,1]
	v_pk_fma_f32 v[28:29], v[60:61], v[56:57], v[28:29] op_sel_hi:[0,1,1]
	v_pk_fma_f32 v[10:11], v[60:61], v[58:59], v[10:11] op_sel_hi:[0,1,1]
	s_waitcnt vmcnt(6)
; #define POOL_ROWS(W) { u32x4 rw[W - 1]; \
;             _Pragma("unroll") for (int j = 1; j < W; ++j) rw[j - 1] = *(const u32x4*)(zr - (size_t)(tk.t - j >= 0 ? j : 0) * DIN); \
;             _Pragma("unroll") for (int j = 1; j < W; ++j) { f32x4 a0, a1; unpack8(rw[j - 1], a0, a1); const float mk = (tk.t - j >= 0) ? 1.0f : 0.0f; s0 += a0 * mk; s1 += a1 * mk; } }
; __device__ void phase_e1(int l) {
;     ...
;         if (gi == 0) POOL_ROWS(2) else if (gi == 1) POOL_ROWS(4) else if (gi == 2) POOL_ROWS(8) else POOL_ROWS(16)
	v_lshlrev_b32_e32 v30, 16, v76
	v_and_b32_e32 v31, 0xffff0000, v76
	v_lshlrev_b32_e32 v32, 16, v77
	v_and_b32_e32 v33, 0xffff0000, v77
	v_lshlrev_b32_e32 v56, 16, v78
	v_and_b32_e32 v57, 0xffff0000, v78
	v_lshlrev_b32_e32 v58, 16, v79
	v_and_b32_e32 v59, 0xffff0000, v79
	v_cndmask_b32_e64 v60, 1.0, 0, s[24:25]
	v_pk_fma_f32 v[8:9], v[60:61], v[32:33], v[8:9] op_sel_hi:[0,1,1]
	v_pk_fma_f32 v[26:27], v[60:61], v[30:31], v[26:27] op_sel_hi:[0,1,1]
	v_pk_fma_f32 v[10:11], v[60:61], v[58:59], v[10:11] op_sel_hi:[0,1,1]
	v_pk_fma_f32 v[28:29], v[60:61], v[56:57], v[28:29] op_sel_hi:[0,1,1]
	s_waitcnt vmcnt(5)
	v_lshlrev_b32_e32 v30, 16, v80
	v_and_b32_e32 v31, 0xffff0000, v80
	v_lshlrev_b32_e32 v32, 16, v81
	v_and_b32_e32 v33, 0xffff0000, v81
	v_lshlrev_b32_e32 v56, 16, v82
	v_and_b32_e32 v57, 0xffff0000, v82
	v_lshlrev_b32_e32 v58, 16, v83
	v_and_b32_e32 v59, 0xffff0000, v83
	v_cndmask_b32_e64 v60, 1.0, 0, s[22:23]
	v_pk_fma_f32 v[26:27], v[60:61], v[30:31], v[26:27] op_sel_hi:[0,1,1]
	v_pk_fma_f32 v[8:9], v[60:61], v[32:33], v[8:9] op_sel_hi:[0,1,1]
	v_pk_fma_f32 v[28:29], v[60:61], v[56:57], v[28:29] op_sel_hi:[0,1,1]
	v_pk_fma_f32 v[10:11], v[60:61], v[58:59], v[10:11] op_sel_hi:[0,1,1]
	s_waitcnt vmcnt(4)
	v_lshlrev_b32_e32 v30, 16, v84
	v_and_b32_e32 v31, 0xffff0000, v84
	v_lshlrev_b32_e32 v32, 16, v85
	v_and_b32_e32 v33, 0xffff0000, v85
	v_lshlrev_b32_e32 v56, 16, v86
	v_and_b32_e32 v57, 0xffff0000, v86
	v_lshlrev_b32_e32 v58, 16, v87
	v_and_b32_e32 v59, 0xffff0000, v87
	v_cndmask_b32_e64 v60, 1.0, 0, s[20:21]
	v_pk_fma_f32 v[8:9], v[60:61], v[32:33], v[8:9] op_sel_hi:[0,1,1]
	v_pk_fma_f32 v[26:27], v[60:61], v[30:31], v[26:27] op_sel_hi:[0,1,1]
	v_pk_fma_f32 v[10:11], v[60:61], v[58:59], v[10:11] op_sel_hi:[0,1,1]
	v_pk_fma_f32 v[28:29], v[60:61], v[56:57], v[28:29] op_sel_hi:[0,1,1]
	s_waitcnt vmcnt(3)
	v_lshlrev_b32_e32 v30, 16, v88
	v_and_b32_e32 v31, 0xffff0000, v88
	v_lshlrev_b32_e32 v32, 16, v89
	v_and_b32_e32 v33, 0xffff0000, v89
	v_lshlrev_b32_e32 v56, 16, v90
	v_and_b32_e32 v57, 0xffff0000, v90
	v_lshlrev_b32_e32 v58, 16, v91
	v_and_b32_e32 v59, 0xffff0000, v91
	v_cndmask_b32_e64 v60, 1.0, 0, s[18:19]
	v_pk_fma_f32 v[26:27], v[60:61], v[30:31], v[26:27] op_sel_hi:[0,1,1]
	v_pk_fma_f32 v[8:9], v[60:61], v[32:33], v[8:9] op_sel_hi:[0,1,1]
	v_pk_fma_f32 v[28:29], v[60:61], v[56:57], v[28:29] op_sel_hi:[0,1,1]
	v_pk_fma_f32 v[10:11], v[60:61], v[58:59], v[10:11] op_sel_hi:[0,1,1]
	s_waitcnt vmcnt(2)
	v_lshlrev_b32_e32 v30, 16, v92
	v_and_b32_e32 v31, 0xffff0000, v92
	v_lshlrev_b32_e32 v32, 16, v93
	v_and_b32_e32 v33, 0xffff0000, v93
	v_lshlrev_b32_e32 v56, 16, v94
	v_and_b32_e32 v57, 0xffff0000, v94
	v_lshlrev_b32_e32 v58, 16, v95
	v_and_b32_e32 v59, 0xffff0000, v95
	v_cndmask_b32_e64 v60, 1.0, 0, s[16:17]
	v_pk_fma_f32 v[8:9], v[60:61], v[32:33], v[8:9] op_sel_hi:[0,1,1]
	v_pk_fma_f32 v[26:27], v[60:61], v[30:31], v[26:27] op_sel_hi:[0,1,1]
	v_pk_fma_f32 v[10:11], v[60:61], v[58:59], v[10:11] op_sel_hi:[0,1,1]
	v_pk_fma_f32 v[28:29], v[60:61], v[56:57], v[28:29] op_sel_hi:[0,1,1]
	s_waitcnt vmcnt(1)
	v_lshlrev_b32_e32 v30, 16, v4
	v_and_b32_e32 v31, 0xffff0000, v4
	v_lshlrev_b32_e32 v4, 16, v5
	v_and_b32_e32 v5, 0xffff0000, v5
	v_lshlrev_b32_e32 v32, 16, v6
	v_and_b32_e32 v33, 0xffff0000, v6
	v_lshlrev_b32_e32 v6, 16, v7
	v_and_b32_e32 v7, 0xffff0000, v7
	v_cndmask_b32_e64 v56, 1.0, 0, s[14:15]
	v_pk_fma_f32 v[26:27], v[56:57], v[30:31], v[26:27] op_sel_hi:[0,1,1]
	v_pk_fma_f32 v[4:5], v[56:57], v[4:5], v[8:9] op_sel_hi:[0,1,1]
	v_pk_fma_f32 v[8:9], v[56:57], v[32:33], v[28:29] op_sel_hi:[0,1,1]
	v_pk_fma_f32 v[6:7], v[56:57], v[6:7], v[10:11] op_sel_hi:[0,1,1]
	s_waitcnt vmcnt(0)
	v_lshlrev_b32_e32 v10, 16, v0
	v_and_b32_e32 v11, 0xffff0000, v0
	v_lshlrev_b32_e32 v0, 16, v1
	v_and_b32_e32 v1, 0xffff0000, v1
	v_lshlrev_b32_e32 v28, 16, v2
	v_and_b32_e32 v29, 0xffff0000, v2
	v_lshlrev_b32_e32 v30, 16, v3
	v_and_b32_e32 v31, 0xffff0000, v3
	v_cndmask_b32_e64 v32, 1.0, 0, s[12:13]
	v_pk_fma_f32 v[2:3], v[32:33], v[0:1], v[4:5] op_sel_hi:[0,1,1]
	v_pk_fma_f32 v[0:1], v[32:33], v[10:11], v[26:27] op_sel_hi:[0,1,1]
	v_pk_fma_f32 v[6:7], v[32:33], v[30:31], v[6:7] op_sel_hi:[0,1,1]
	v_pk_fma_f32 v[4:5], v[32:33], v[28:29], v[8:9] op_sel_hi:[0,1,1]

; __device__ __forceinline__ void unpack8(const u32x4 w, f32x4& v0, f32x4& v1) { v0 = (f32x4){bflo(w.x), bfhi(w.x), bflo(w.y), bfhi(w.y)}; v1 = (f32x4){bflo(w.z), bfhi(w.z), bflo(w.w), bfhi(w.w)}; }
; __device__ __forceinline__ Tok tok_decode(int tok) { Tok r; if (tok < T_P) { r.is_s = 0; r.seq = tok >> 11; r.t = tok & 2047; } else { r.is_s = 1; r.seq = (tok - T_P) >> 3; r.t = (tok - T_P) & 7; } return r; }
; #define POOL_ROWS(W) { u32x4 rw[W - 1]; \
;             _Pragma("unroll") for (int j = 1; j < W; ++j) rw[j - 1] = *(const u32x4*)(zr - (size_t)(tk.t - j >= 0 ? j : 0) * DIN); \
;             _Pragma("unroll") for (int j = 1; j < W; ++j) { f32x4 a0, a1; unpack8(rw[j - 1], a0, a1); const float mk = (tk.t - j >= 0) ? 1.0f : 0.0f; s0 += a0 * mk; s1 += a1 * mk; } }
; __device__ void phase_e1(int l) {
;     ...
;         const int gi = (it >> 6) & 3, tok = (it >> 8) * 4 + ((it >> 4) & 3), c = gi * 128 + (it & 15) * 8, win = 2 << gi; const Tok tk = tok_decode(tok);
;         const bf16_t* zr = z + (size_t)tok * DIN + O_U + c;
;         f32x4 u0, u1; unpack8(*(const u32x4*)zr, u0, u1);
;         f32x4 s0 = u0, s1 = u1;
;     ...
;         if (gi == 0) POOL_ROWS(2) else if (gi == 1) POOL_ROWS(4) else if (gi == 2) POOL_ROWS(8) else POOL_ROWS(16)
.LBB0_1374:
	v_ashrrev_i32_e32 v19, 6, v51
	s_waitcnt vmcnt(2)
	v_lshrrev_b32_e32 v0, 4, v51
	v_bfi_b32 v18, -4, v19, v0
	v_lshlrev_b32_e32 v0, 3, v51
	v_cmp_gt_i32_e32 vcc, s7, v18
	v_bfe_u32 v53, v51, 6, 2
	v_bfe_i32 v255, v51, 8, 1
	v_and_b32_e32 v255, 3, v255
	v_xor_b32_e32 v53, v53, v255
	s_waitcnt vmcnt(1)
	v_and_b32_e32 v4, -4, v19
	v_and_b32_e32 v0, 0x78, v0
	v_bfe_u32 v5, v51, 4, 2
	v_cndmask_b32_e32 v6, 7, v13, vcc
	v_lshl_or_b32 v52, v53, 7, v0
	v_bitop3_b32 v54, v6, v4, v5 bitop3:0xe0
	v_mad_i64_i32 v[0:1], s[10:11], v18, s8, v[14:15]
	v_lshlrev_b32_e32 v16, 1, v52
	v_cmp_eq_u32_e64 s[12:13], 0, v54
	v_lshl_add_u64 v[28:29], v[0:1], 0, v[16:17]
	global_load_dwordx4 v[0:3], v[28:29], off offset:3584
	v_cndmask_b32_e64 v5, -1, 0, s[12:13]
	v_cndmask_b32_e64 v4, v36, 0, s[12:13]
	v_lshl_add_u64 v[4:5], v[28:29], 0, v[4:5]
	global_load_dwordx4 v[8:11], v[4:5], off offset:3584
	v_cmp_lt_i32_e64 s[10:11], s6, v18
	v_cmp_lt_i32_e64 s[14:15], 1, v53
	s_waitcnt vmcnt(1)
	v_lshlrev_b32_e32 v22, 16, v0
	v_and_b32_e32 v23, 0xffff0000, v0
	v_lshlrev_b32_e32 v26, 16, v1
	v_and_b32_e32 v27, 0xffff0000, v1
	v_lshlrev_b32_e32 v20, 16, v2
	v_and_b32_e32 v21, 0xffff0000, v2
	v_lshlrev_b32_e32 v24, 16, v3
	v_and_b32_e32 v25, 0xffff0000, v3
	s_and_saveexec_b64 s[16:17], s[14:15]
	s_xor_b64 s[68:69], exec, s[16:17]
	s_cbranch_execz .LBB0_1380
	v_cmp_lt_i32_e64 s[14:15], 2, v53
	s_and_saveexec_b64 s[16:17], s[14:15]
	s_xor_b64 s[70:71], exec, s[16:17]
	s_cbranch_execz .LBB0_1377
	v_cmp_gt_u32_e64 s[42:43], 2, v54
	v_cmp_gt_u32_e64 s[38:39], 4, v54
	v_cmp_gt_u32_e64 s[40:41], 3, v54
	v_cndmask_b32_e64 v1, -1, 0, s[42:43]
	v_cndmask_b32_e64 v0, v37, 0, s[42:43]
	v_cndmask_b32_e64 v3, -1, 0, s[38:39]
	v_cndmask_b32_e64 v2, v39, 0, s[38:39]
	v_lshl_add_u64 v[0:1], v[28:29], 0, v[0:1]
	v_lshl_add_u64 v[2:3], v[28:29], 0, v[2:3]
	global_load_dwordx4 v[30:33], v[0:1], off offset:3584
	global_load_dwordx4 v[60:63], v[2:3], off offset:3584
	v_cndmask_b32_e64 v1, -1, 0, s[40:41]
	v_cndmask_b32_e64 v0, v38, 0, s[40:41]
	v_cmp_gt_u32_e64 s[36:37], 5, v54
	v_lshl_add_u64 v[0:1], v[28:29], 0, v[0:1]
	v_cmp_gt_u32_e64 s[34:35], 6, v54
	v_cndmask_b32_e64 v5, -1, 0, s[36:37]
	global_load_dwordx4 v[56:59], v[0:1], off offset:3584
	v_cndmask_b32_e64 v4, v40, 0, s[36:37]
	v_cndmask_b32_e64 v7, -1, 0, s[34:35]
	v_cmp_gt_u32_e64 s[30:31], 7, v54
	v_lshl_add_u64 v[4:5], v[28:29], 0, v[4:5]
	v_cndmask_b32_e64 v6, v41, 0, s[34:35]
	v_cmp_gt_u32_e64 s[26:27], 9, v54
	global_load_dwordx4 v[64:67], v[4:5], off offset:3584
	v_cndmask_b32_e64 v1, -1, 0, s[30:31]
	v_cndmask_b32_e64 v0, v42, 0, s[30:31]
	v_lshl_add_u64 v[6:7], v[28:29], 0, v[6:7]
	v_cndmask_b32_e64 v69, -1, 0, s[26:27]
	s_waitcnt vmcnt(4)
	v_lshlrev_b32_e32 v70, 16, v8
	v_and_b32_e32 v71, 0xffff0000, v8
	v_lshlrev_b32_e32 v82, 16, v9
	v_and_b32_e32 v83, 0xffff0000, v9
	v_lshlrev_b32_e32 v4, 16, v10
	v_and_b32_e32 v5, 0xffff0000, v10
	v_lshlrev_b32_e32 v84, 16, v11
	v_and_b32_e32 v85, 0xffff0000, v11
	v_cndmask_b32_e64 v86, 1.0, 0, s[12:13]
	v_cndmask_b32_e64 v68, v44, 0, s[26:27]
	global_load_dwordx4 v[8:11], v[6:7], off offset:3584
	v_lshl_add_u64 v[0:1], v[28:29], 0, v[0:1]
	v_pk_fma_f32 v[98:99], v[86:87], v[70:71], v[22:23] op_sel_hi:[0,1,1]
	v_lshl_add_u64 v[6:7], v[28:29], 0, v[68:69]
	global_load_dwordx4 v[68:71], v[0:1], off offset:3584
	v_cmp_gt_u32_e64 s[28:29], 8, v54
	v_cmp_gt_u32_e64 s[24:25], 10, v54
	v_cmp_gt_u32_e64 s[20:21], 12, v54
	v_cmp_gt_u32_e64 s[18:19], 13, v54
	v_cndmask_b32_e64 v35, -1, 0, s[28:29]
	v_cndmask_b32_e64 v73, -1, 0, s[24:25]
	v_cmp_gt_u32_e64 s[22:23], 11, v54
	v_cndmask_b32_e64 v3, -1, 0, s[20:21]
	v_cndmask_b32_e64 v77, -1, 0, s[18:19]
	v_cmp_gt_u32_e64 s[16:17], 14, v54
	v_cmp_gt_u32_e64 s[14:15], 15, v54
	v_cndmask_b32_e64 v34, v43, 0, s[28:29]
	v_cndmask_b32_e64 v72, v45, 0, s[24:25]
	v_cndmask_b32_e64 v2, v47, 0, s[20:21]
	v_cndmask_b32_e64 v76, v48, 0, s[18:19]
	v_cndmask_b32_e64 v75, -1, 0, s[22:23]
	v_cndmask_b32_e64 v79, -1, 0, s[16:17]
	v_cndmask_b32_e64 v81, -1, 0, s[14:15]
	v_cndmask_b32_e64 v74, v46, 0, s[22:23]
	v_cndmask_b32_e64 v78, v49, 0, s[16:17]
	v_cndmask_b32_e64 v80, v50, 0, s[14:15]
	v_pk_fma_f32 v[102:103], v[86:87], v[4:5], v[20:21] op_sel_hi:[0,1,1]
	v_lshl_add_u64 v[4:5], v[28:29], 0, v[34:35]
	v_lshl_add_u64 v[0:1], v[28:29], 0, v[72:73]
	v_lshl_add_u64 v[2:3], v[28:29], 0, v[2:3]
	v_lshl_add_u64 v[92:93], v[28:29], 0, v[76:77]
	v_pk_fma_f32 v[96:97], v[86:87], v[82:83], v[26:27] op_sel_hi:[0,1,1]
	v_pk_fma_f32 v[100:101], v[86:87], v[84:85], v[24:25] op_sel_hi:[0,1,1]
	v_lshl_add_u64 v[34:35], v[28:29], 0, v[74:75]
	v_lshl_add_u64 v[104:105], v[28:29], 0, v[78:79]
	v_lshl_add_u64 v[28:29], v[28:29], 0, v[80:81]
	global_load_dwordx4 v[72:75], v[4:5], off offset:3584
	global_load_dwordx4 v[76:79], v[6:7], off offset:3584
	global_load_dwordx4 v[80:83], v[0:1], off offset:3584
	global_load_dwordx4 v[84:87], v[34:35], off offset:3584
	global_load_dwordx4 v[88:91], v[2:3], off offset:3584
	s_nop 0
	global_load_dwordx4 v[92:95], v[92:93], off offset:3584
	s_nop 0
	global_load_dwordx4 v[4:7], v[104:105], off offset:3584
	global_load_dwordx4 v[0:3], v[28:29], off offset:3584
	v_cndmask_b32_e64 v104, 1.0, 0, s[42:43]
	s_waitcnt vmcnt(13)
	v_lshlrev_b32_e32 v28, 16, v30
	v_and_b32_e32 v29, 0xffff0000, v30
	v_lshlrev_b32_e32 v30, 16, v31
	v_and_b32_e32 v31, 0xffff0000, v31
	v_lshlrev_b32_e32 v34, 16, v32
	v_and_b32_e32 v35, 0xffff0000, v32
	v_lshlrev_b32_e32 v32, 16, v33
	v_and_b32_e32 v33, 0xffff0000, v33
	v_pk_fma_f32 v[28:29], v[104:105], v[28:29], v[98:99] op_sel_hi:[0,1,1]
	v_pk_fma_f32 v[30:31], v[104:105], v[30:31], v[96:97] op_sel_hi:[0,1,1]
	v_pk_fma_f32 v[34:35], v[104:105], v[34:35], v[102:103] op_sel_hi:[0,1,1]
	v_pk_fma_f32 v[32:33], v[104:105], v[32:33], v[100:101] op_sel_hi:[0,1,1]
	s_waitcnt vmcnt(11)
; #define POOL_ROWS(W) { u32x4 rw[W - 1]; \
;             _Pragma("unroll") for (int j = 1; j < W; ++j) rw[j - 1] = *(const u32x4*)(zr - (size_t)(tk.t - j >= 0 ? j : 0) * DIN); \
;             _Pragma("unroll") for (int j = 1; j < W; ++j) { f32x4 a0, a1; unpack8(rw[j - 1], a0, a1); const float mk = (tk.t - j >= 0) ? 1.0f : 0.0f; s0 += a0 * mk; s1 += a1 * mk; } }
; __device__ void phase_e1(int l) {
;     ...
;         if (gi == 0) POOL_ROWS(2) else if (gi == 1) POOL_ROWS(4) else if (gi == 2) POOL_ROWS(8) else POOL_ROWS(16)
	v_lshlrev_b32_e32 v96, 16, v56
	v_and_b32_e32 v97, 0xffff0000, v56
	v_lshlrev_b32_e32 v56, 16, v57
	v_and_b32_e32 v57, 0xffff0000, v57
	v_lshlrev_b32_e32 v98, 16, v58
	v_and_b32_e32 v99, 0xffff0000, v58
	v_lshlrev_b32_e32 v58, 16, v59
	v_and_b32_e32 v59, 0xffff0000, v59
	v_cndmask_b32_e64 v100, 1.0, 0, s[40:41]
	v_pk_fma_f32 v[30:31], v[100:101], v[56:57], v[30:31] op_sel_hi:[0,1,1]
	v_pk_fma_f32 v[28:29], v[100:101], v[96:97], v[28:29] op_sel_hi:[0,1,1]
	v_pk_fma_f32 v[32:33], v[100:101], v[58:59], v[32:33] op_sel_hi:[0,1,1]
	v_pk_fma_f32 v[34:35], v[100:101], v[98:99], v[34:35] op_sel_hi:[0,1,1]
	v_lshlrev_b32_e32 v56, 16, v60
	v_and_b32_e32 v57, 0xffff0000, v60
	v_lshlrev_b32_e32 v58, 16, v61
	v_and_b32_e32 v59, 0xffff0000, v61
	v_lshlrev_b32_e32 v60, 16, v62
	v_and_b32_e32 v61, 0xffff0000, v62
	v_lshlrev_b32_e32 v62, 16, v63
	v_and_b32_e32 v63, 0xffff0000, v63
	v_cndmask_b32_e64 v96, 1.0, 0, s[38:39]
	v_pk_fma_f32 v[28:29], v[96:97], v[56:57], v[28:29] op_sel_hi:[0,1,1]
	v_pk_fma_f32 v[30:31], v[96:97], v[58:59], v[30:31] op_sel_hi:[0,1,1]
	v_pk_fma_f32 v[34:35], v[96:97], v[60:61], v[34:35] op_sel_hi:[0,1,1]
	v_pk_fma_f32 v[32:33], v[96:97], v[62:63], v[32:33] op_sel_hi:[0,1,1]
	s_waitcnt vmcnt(10)
	v_lshlrev_b32_e32 v56, 16, v64
	v_and_b32_e32 v57, 0xffff0000, v64
	v_lshlrev_b32_e32 v58, 16, v65
	v_and_b32_e32 v59, 0xffff0000, v65
	v_lshlrev_b32_e32 v60, 16, v66
	v_and_b32_e32 v61, 0xffff0000, v66
	v_lshlrev_b32_e32 v62, 16, v67
	v_and_b32_e32 v63, 0xffff0000, v67
	v_cndmask_b32_e64 v64, 1.0, 0, s[36:37]
	v_pk_fma_f32 v[30:31], v[64:65], v[58:59], v[30:31] op_sel_hi:[0,1,1]
	v_pk_fma_f32 v[28:29], v[64:65], v[56:57], v[28:29] op_sel_hi:[0,1,1]
	v_pk_fma_f32 v[32:33], v[64:65], v[62:63], v[32:33] op_sel_hi:[0,1,1]
	v_pk_fma_f32 v[34:35], v[64:65], v[60:61], v[34:35] op_sel_hi:[0,1,1]
	s_waitcnt vmcnt(9)
	v_lshlrev_b32_e32 v56, 16, v8
	v_and_b32_e32 v57, 0xffff0000, v8
	v_lshlrev_b32_e32 v8, 16, v9
	v_and_b32_e32 v9, 0xffff0000, v9
	v_lshlrev_b32_e32 v58, 16, v10
	v_and_b32_e32 v59, 0xffff0000, v10
	v_lshlrev_b32_e32 v10, 16, v11
	v_and_b32_e32 v11, 0xffff0000, v11
	v_cndmask_b32_e64 v60, 1.0, 0, s[34:35]
	v_pk_fma_f32 v[28:29], v[60:61], v[56:57], v[28:29] op_sel_hi:[0,1,1]
	v_pk_fma_f32 v[8:9], v[60:61], v[8:9], v[30:31] op_sel_hi:[0,1,1]
	v_pk_fma_f32 v[30:31], v[60:61], v[58:59], v[34:35] op_sel_hi:[0,1,1]
	v_pk_fma_f32 v[10:11], v[60:61], v[10:11], v[32:33] op_sel_hi:[0,1,1]
	s_waitcnt vmcnt(8)
	v_lshlrev_b32_e32 v32, 16, v68
	v_and_b32_e32 v33, 0xffff0000, v68
	v_lshlrev_b32_e32 v34, 16, v69
	v_and_b32_e32 v35, 0xffff0000, v69
	v_lshlrev_b32_e32 v56, 16, v70
	v_and_b32_e32 v57, 0xffff0000, v70
	v_lshlrev_b32_e32 v58, 16, v71
	v_and_b32_e32 v59, 0xffff0000, v71
	v_cndmask_b32_e64 v60, 1.0, 0, s[30:31]
	v_pk_fma_f32 v[8:9], v[60:61], v[34:35], v[8:9] op_sel_hi:[0,1,1]
	v_pk_fma_f32 v[28:29], v[60:61], v[32:33], v[28:29] op_sel_hi:[0,1,1]
	v_pk_fma_f32 v[10:11], v[60:61], v[58:59], v[10:11] op_sel_hi:[0,1,1]
	v_pk_fma_f32 v[30:31], v[60:61], v[56:57], v[30:31] op_sel_hi:[0,1,1]
	s_waitcnt vmcnt(7)
	v_lshlrev_b32_e32 v32, 16, v72
	v_and_b32_e32 v33, 0xffff0000, v72
	v_lshlrev_b32_e32 v34, 16, v73
	v_and_b32_e32 v35, 0xffff0000, v73
	v_lshlrev_b32_e32 v56, 16, v74
	v_and_b32_e32 v57, 0xffff0000, v74
	v_lshlrev_b32_e32 v58, 16, v75
	v_and_b32_e32 v59, 0xffff0000, v75
	v_cndmask_b32_e64 v60, 1.0, 0, s[28:29]
	v_pk_fma_f32 v[28:29], v[60:61], v[32:33], v[28:29] op_sel_hi:[0,1,1]
	v_pk_fma_f32 v[8:9], v[60:61], v[34:35], v[8:9] op_sel_hi:[0,1,1]
	v_pk_fma_f32 v[30:31], v[60:61], v[56:57], v[30:31] op_sel_hi:[0,1,1]
	v_pk_fma_f32 v[10:11], v[60:61], v[58:59], v[10:11] op_sel_hi:[0,1,1]
	s_waitcnt vmcnt(6)
; #define POOL_ROWS(W) { u32x4 rw[W - 1]; \
;             _Pragma("unroll") for (int j = 1; j < W; ++j) rw[j - 1] = *(const u32x4*)(zr - (size_t)(tk.t - j >= 0 ? j : 0) * DIN); \
;             _Pragma("unroll") for (int j = 1; j < W; ++j) { f32x4 a0, a1; unpack8(rw[j - 1], a0, a1); const float mk = (tk.t - j >= 0) ? 1.0f : 0.0f; s0 += a0 * mk; s1 += a1 * mk; } }
; __device__ void phase_e1(int l) {
;     ...
;         if (gi == 0) POOL_ROWS(2) else if (gi == 1) POOL_ROWS(4) else if (gi == 2) POOL_ROWS(8) else POOL_ROWS(16)
	v_lshlrev_b32_e32 v32, 16, v76
	v_and_b32_e32 v33, 0xffff0000, v76
	v_lshlrev_b32_e32 v34, 16, v77
	v_and_b32_e32 v35, 0xffff0000, v77
	v_lshlrev_b32_e32 v56, 16, v78
	v_and_b32_e32 v57, 0xffff0000, v78
	v_lshlrev_b32_e32 v58, 16, v79
	v_and_b32_e32 v59, 0xffff0000, v79
	v_cndmask_b32_e64 v60, 1.0, 0, s[26:27]
	v_pk_fma_f32 v[8:9], v[60:61], v[34:35], v[8:9] op_sel_hi:[0,1,1]
	v_pk_fma_f32 v[28:29], v[60:61], v[32:33], v[28:29] op_sel_hi:[0,1,1]
	v_pk_fma_f32 v[10:11], v[60:61], v[58:59], v[10:11] op_sel_hi:[0,1,1]
	v_pk_fma_f32 v[30:31], v[60:61], v[56:57], v[30:31] op_sel_hi:[0,1,1]
	s_waitcnt vmcnt(5)
	v_lshlrev_b32_e32 v32, 16, v80
	v_and_b32_e32 v33, 0xffff0000, v80
	v_lshlrev_b32_e32 v34, 16, v81
	v_and_b32_e32 v35, 0xffff0000, v81
	v_lshlrev_b32_e32 v56, 16, v82
	v_and_b32_e32 v57, 0xffff0000, v82
	v_lshlrev_b32_e32 v58, 16, v83
	v_and_b32_e32 v59, 0xffff0000, v83
	v_cndmask_b32_e64 v60, 1.0, 0, s[24:25]
	v_pk_fma_f32 v[28:29], v[60:61], v[32:33], v[28:29] op_sel_hi:[0,1,1]
	v_pk_fma_f32 v[8:9], v[60:61], v[34:35], v[8:9] op_sel_hi:[0,1,1]
	v_pk_fma_f32 v[30:31], v[60:61], v[56:57], v[30:31] op_sel_hi:[0,1,1]
	v_pk_fma_f32 v[10:11], v[60:61], v[58:59], v[10:11] op_sel_hi:[0,1,1]
	s_waitcnt vmcnt(4)
	v_lshlrev_b32_e32 v32, 16, v84
	v_and_b32_e32 v33, 0xffff0000, v84
	v_lshlrev_b32_e32 v34, 16, v85
	v_and_b32_e32 v35, 0xffff0000, v85
	v_lshlrev_b32_e32 v56, 16, v86
	v_and_b32_e32 v57, 0xffff0000, v86
	v_lshlrev_b32_e32 v58, 16, v87
	v_and_b32_e32 v59, 0xffff0000, v87
	v_cndmask_b32_e64 v60, 1.0, 0, s[22:23]
	v_pk_fma_f32 v[8:9], v[60:61], v[34:35], v[8:9] op_sel_hi:[0,1,1]
	v_pk_fma_f32 v[28:29], v[60:61], v[32:33], v[28:29] op_sel_hi:[0,1,1]
	v_pk_fma_f32 v[10:11], v[60:61], v[58:59], v[10:11] op_sel_hi:[0,1,1]
	v_pk_fma_f32 v[30:31], v[60:61], v[56:57], v[30:31] op_sel_hi:[0,1,1]
	s_waitcnt vmcnt(3)
	v_lshlrev_b32_e32 v32, 16, v88
	v_and_b32_e32 v33, 0xffff0000, v88
	v_lshlrev_b32_e32 v34, 16, v89
	v_and_b32_e32 v35, 0xffff0000, v89
	v_lshlrev_b32_e32 v56, 16, v90
	v_and_b32_e32 v57, 0xffff0000, v90
	v_lshlrev_b32_e32 v58, 16, v91
	v_and_b32_e32 v59, 0xffff0000, v91
	v_cndmask_b32_e64 v60, 1.0, 0, s[20:21]
	v_pk_fma_f32 v[28:29], v[60:61], v[32:33], v[28:29] op_sel_hi:[0,1,1]
	v_pk_fma_f32 v[8:9], v[60:61], v[34:35], v[8:9] op_sel_hi:[0,1,1]
	v_pk_fma_f32 v[30:31], v[60:61], v[56:57], v[30:31] op_sel_hi:[0,1,1]
	v_pk_fma_f32 v[10:11], v[60:61], v[58:59], v[10:11] op_sel_hi:[0,1,1]
	s_waitcnt vmcnt(2)
	v_lshlrev_b32_e32 v32, 16, v92
	v_and_b32_e32 v33, 0xffff0000, v92
	v_lshlrev_b32_e32 v34, 16, v93
	v_and_b32_e32 v35, 0xffff0000, v93
	v_lshlrev_b32_e32 v56, 16, v94
	v_and_b32_e32 v57, 0xffff0000, v94
	v_lshlrev_b32_e32 v58, 16, v95
	v_and_b32_e32 v59, 0xffff0000, v95
	v_cndmask_b32_e64 v60, 1.0, 0, s[18:19]
	v_pk_fma_f32 v[8:9], v[60:61], v[34:35], v[8:9] op_sel_hi:[0,1,1]
	v_pk_fma_f32 v[28:29], v[60:61], v[32:33], v[28:29] op_sel_hi:[0,1,1]
	v_pk_fma_f32 v[10:11], v[60:61], v[58:59], v[10:11] op_sel_hi:[0,1,1]
	v_pk_fma_f32 v[30:31], v[60:61], v[56:57], v[30:31] op_sel_hi:[0,1,1]
	s_waitcnt vmcnt(1)
	v_lshlrev_b32_e32 v32, 16, v4
	v_and_b32_e32 v33, 0xffff0000, v4
	v_lshlrev_b32_e32 v4, 16, v5
	v_and_b32_e32 v5, 0xffff0000, v5
	v_lshlrev_b32_e32 v34, 16, v6
	v_and_b32_e32 v35, 0xffff0000, v6
	v_lshlrev_b32_e32 v6, 16, v7
	v_and_b32_e32 v7, 0xffff0000, v7
	v_cndmask_b32_e64 v56, 1.0, 0, s[16:17]
	v_pk_fma_f32 v[28:29], v[56:57], v[32:33], v[28:29] op_sel_hi:[0,1,1]
	v_pk_fma_f32 v[4:5], v[56:57], v[4:5], v[8:9] op_sel_hi:[0,1,1]
	v_pk_fma_f32 v[8:9], v[56:57], v[34:35], v[30:31] op_sel_hi:[0,1,1]
	v_pk_fma_f32 v[6:7], v[56:57], v[6:7], v[10:11] op_sel_hi:[0,1,1]
	s_waitcnt vmcnt(0)
	v_lshlrev_b32_e32 v10, 16, v0
	v_and_b32_e32 v11, 0xffff0000, v0
	v_lshlrev_b32_e32 v0, 16, v1
	v_and_b32_e32 v1, 0xffff0000, v1
	v_lshlrev_b32_e32 v30, 16, v2
	v_and_b32_e32 v31, 0xffff0000, v2
	v_lshlrev_b32_e32 v32, 16, v3
	v_and_b32_e32 v33, 0xffff0000, v3
	v_cndmask_b32_e64 v34, 1.0, 0, s[14:15]
	v_pk_fma_f32 v[2:3], v[34:35], v[0:1], v[4:5] op_sel_hi:[0,1,1]
	v_pk_fma_f32 v[0:1], v[34:35], v[10:11], v[28:29] op_sel_hi:[0,1,1]
	v_pk_fma_f32 v[6:7], v[34:35], v[32:33], v[6:7] op_sel_hi:[0,1,1]
	v_pk_fma_f32 v[4:5], v[34:35], v[30:31], v[8:9] op_sel_hi:[0,1,1]
